# P0 leftover weight items moved to WGs 192-255 (reversed wave numbering)
# speedup vs baseline: 1.0254x; 1.0254x over previous
.LBB0_17:
	s_lshr_b32 s90, s79, 6
	s_lshl_b32 s0, s2, 3
	s_add_i32 s42, s90, s0
	s_lshl_b32 s74, s86, 3
	s_add_u32 s84, s68, 0x100000
	s_addc_u32 s85, s69, 0
	s_add_u32 s88, s68, 0xf00000
	s_addc_u32 s89, s69, 0
	s_add_u32 s92, s68, 0x1300000
	s_addc_u32 s93, s69, 0
	s_add_u32 s80, s68, 0x1500000
	s_addc_u32 s81, s69, 0
	s_cmp_lt_i32 s70, 1
	s_cselect_b64 s[0:1], -1, 0
	s_cmp_gt_i32 s71, 0
	s_cselect_b64 s[4:5], -1, 0
	s_and_b64 s[0:1], s[0:1], s[4:5]
	s_andn2_b64 vcc, exec, s[0:1]
	v_and_b32_e32 v200, 63, v201
	s_cbranch_vccnz .LBB0_168
	s_cmpk_gt_i32 s42, 0x11ff
	s_cbranch_scc1 .LBB0_88
	v_lshlrev_b32_e32 v0, 2, v201
	v_and_b32_e32 v66, 28, v0
	v_mov_b32_e32 v69, 0
	v_lshlrev_b32_e32 v0, 13, v201
	s_sub_i32 s32, 0x7ff, s42
	s_lshl_b32 s0, s32, 1
	v_and_b32_e32 v64, 56, v201
	v_and_b32_e32 v65, 0xe000, v0
	s_lshl_b32 s3, s86, 4
	s_lshl_b32 s33, s32, 5
	s_lshl_b32 s34, s86, 9
	s_lshl_b32 s35, s32, 16
	s_lshl_b32 s36, s86, 20
	s_add_i32 s37, s0, 0x1e400
	s_lshl_b32 s38, s86, 5
	s_lshl_b32 s39, s86, 19
	s_lshl_b32 s40, s86, 8
	s_mov_b32 s1, 0
	s_movk_i32 s41, 0x7000
	v_lshlrev_b32_e32 v68, 2, v66
	s_mov_b64 s[4:5], 0x1000
	s_mov_b64 s[6:7], 0x2000
	s_mov_b64 s[8:9], 0x3000
	s_mov_b64 s[10:11], 0x800
	s_mov_b64 s[12:13], 0x1800
	s_mov_b32 s43, s32
	v_mov_b32_e32 v0, v69
	v_mov_b32_e32 v1, v69
	v_mov_b32_e32 v2, v69
	v_mov_b32_e32 v3, v69
	v_mov_b32_e32 v4, v69
	v_mov_b32_e32 v5, v69
	v_mov_b32_e32 v6, v69
	v_mov_b32_e32 v7, v69
	v_mov_b32_e32 v8, v69
	v_mov_b32_e32 v9, v69
	v_mov_b32_e32 v10, v69
	v_mov_b32_e32 v11, v69
	v_mov_b32_e32 v12, v69
	v_mov_b32_e32 v13, v69
	v_mov_b32_e32 v14, v69
	v_mov_b32_e32 v15, v69
	v_mov_b32_e32 v16, v69
	v_mov_b32_e32 v17, v69
	v_mov_b32_e32 v18, v69
	v_mov_b32_e32 v19, v69
	v_mov_b32_e32 v20, v69
	v_mov_b32_e32 v21, v69
	v_mov_b32_e32 v22, v69
	v_mov_b32_e32 v23, v69
	v_mov_b32_e32 v24, v69
	v_mov_b32_e32 v25, v69
	v_mov_b32_e32 v26, v69
	v_mov_b32_e32 v27, v69
	v_mov_b32_e32 v28, v69
	v_mov_b32_e32 v29, v69
	v_mov_b32_e32 v30, v69
	v_mov_b32_e32 v31, v69
	s_branch .LBB0_22
